# RWKV scan step reordered: y chain, T and reduce-scatter ops fill the two wait states before every dependent DPP add (restores VALU-to-DPP hazard distance lost when the LDS reads moved to the step top)
# speedup vs baseline: 1.0083x; 1.0083x over previous
.Lscan_chunk:
	ds_read_b128 v[96:99], v139 offset:3456
	ds_read_b32 v104, v140 offset:2688
	ds_read_b128 v[88:91], v139 offset:2944
	ds_read_b128 v[84:87], v139 offset:2688
	ds_read_b128 v[92:95], v139 offset:3200
	ds_read_b128 v[100:103], v139 offset:3712
	v_pk_mul_f32 v[16:17], v[0:1], v[44:45]
	v_pk_fma_f32 v[16:17], v[2:3], v[46:47], v[16:17]
	v_add_f32_e32 v18, v16, v17
	v_pk_mul_f32 v[20:21], v[0:1], v[122:123]
	v_pk_fma_f32 v[4:5], v[0:1], v[40:41], v[8:9]
	v_add_f32_dpp v18, v18, v18 quad_perm:[1,0,3,2] row_mask:0xf bank_mask:0xf bound_ctrl:1
	v_pk_fma_f32 v[20:21], v[2:3], v[124:125], v[20:21]
	v_add_f32_e32 v201, v20, v21
	v_add_f32_dpp v18, v18, v18 quad_perm:[2,3,0,1] row_mask:0xf bank_mask:0xf bound_ctrl:1
	s_nop 0
	v_pk_fma_f32 v[6:7], v[2:3], v[42:43], v[10:11]
	v_add_f32_dpp v18, v18, v18 row_half_mirror row_mask:0xf bank_mask:0xf bound_ctrl:1
	v_add_f32_dpp v201, v201, v201 row_ror:8 row_mask:0xf bank_mask:0xc bound_ctrl:1
	v_add_f32_dpp v201, v191, v191 row_ror:8 row_mask:0xf bank_mask:0x3 bound_ctrl:1
	v_add_f32_dpp v18, v18, v18 row_ror:8 row_mask:0xf bank_mask:0xf bound_ctrl:1
	v_pk_fma_f32 v[0:1], v[48:49], v[18:19], v[4:5] op_sel_hi:[1,0,1] neg_lo:[1,0,0] neg_hi:[1,0,0]
	v_pk_fma_f32 v[2:3], v[50:51], v[18:19], v[6:7] op_sel_hi:[1,0,1] neg_lo:[1,0,0] neg_hi:[1,0,0]
	s_waitcnt lgkmcnt(6)
	v_pk_mul_f32 v[8:9], v[74:75], v[82:83] op_sel_hi:[1,0]
	v_pk_mul_f32 v[10:11], v[76:77], v[82:83] op_sel_hi:[1,0]
	ds_read_b128 v[118:121], v139 offset:4800
	ds_read_b32 v126, v140 offset:4032
	ds_read_b128 v[110:113], v139 offset:4288
	ds_read_b128 v[106:109], v139 offset:4032
	ds_read_b128 v[114:117], v139 offset:4544
	ds_read_b128 v[122:125], v139 offset:5056
	v_pk_mul_f32 v[16:17], v[0:1], v[66:67]
	v_pk_fma_f32 v[16:17], v[2:3], v[68:69], v[16:17]
	v_add_f32_e32 v18, v16, v17
	v_pk_mul_f32 v[20:21], v[0:1], v[56:57]
	v_pk_fma_f32 v[4:5], v[0:1], v[62:63], v[8:9]
	v_add_f32_dpp v18, v18, v18 quad_perm:[1,0,3,2] row_mask:0xf bank_mask:0xf bound_ctrl:1
	v_pk_fma_f32 v[20:21], v[2:3], v[58:59], v[20:21]
	v_add_f32_e32 v12, v20, v21
	v_add_f32_dpp v18, v18, v18 quad_perm:[2,3,0,1] row_mask:0xf bank_mask:0xf bound_ctrl:1
	v_add_f32_dpp v196, v196, v196 row_half_mirror row_mask:0xf bank_mask:0xa bound_ctrl:1
	v_pk_fma_f32 v[6:7], v[2:3], v[64:65], v[10:11]
	v_add_f32_dpp v18, v18, v18 row_half_mirror row_mask:0xf bank_mask:0xf bound_ctrl:1
	v_add_f32_dpp v196, v192, v192 row_half_mirror row_mask:0xf bank_mask:0x5 bound_ctrl:1
	v_add_f32_dpp v197, v197, v197 row_half_mirror row_mask:0xf bank_mask:0xa bound_ctrl:1
	v_add_f32_dpp v18, v18, v18 row_ror:8 row_mask:0xf bank_mask:0xf bound_ctrl:1
	v_pk_fma_f32 v[0:1], v[70:71], v[18:19], v[4:5] op_sel_hi:[1,0,1] neg_lo:[1,0,0] neg_hi:[1,0,0]
	v_pk_fma_f32 v[2:3], v[72:73], v[18:19], v[6:7] op_sel_hi:[1,0,1] neg_lo:[1,0,0] neg_hi:[1,0,0]
	s_waitcnt lgkmcnt(6)
	v_pk_mul_f32 v[8:9], v[96:97], v[104:105] op_sel_hi:[1,0]
	v_pk_mul_f32 v[10:11], v[98:99], v[104:105] op_sel_hi:[1,0]
	ds_read_b128 v[52:55], v139 offset:6144
	ds_read_b32 v60, v140 offset:5376
	ds_read_b128 v[44:47], v139 offset:5632
	ds_read_b128 v[40:43], v139 offset:5376
	ds_read_b128 v[48:51], v139 offset:5888
	ds_read_b128 v[56:59], v139 offset:6400
	v_pk_mul_f32 v[16:17], v[0:1], v[88:89]
	v_pk_fma_f32 v[16:17], v[2:3], v[90:91], v[16:17]
	v_add_f32_e32 v18, v16, v17
	v_pk_mul_f32 v[20:21], v[0:1], v[78:79]
	v_pk_fma_f32 v[4:5], v[0:1], v[84:85], v[8:9]
	v_add_f32_dpp v18, v18, v18 quad_perm:[1,0,3,2] row_mask:0xf bank_mask:0xf bound_ctrl:1
	v_pk_fma_f32 v[20:21], v[2:3], v[80:81], v[20:21]
	v_add_f32_e32 v13, v20, v21
	v_add_f32_dpp v18, v18, v18 quad_perm:[2,3,0,1] row_mask:0xf bank_mask:0xf bound_ctrl:1
	v_add_f32_dpp v197, v193, v193 row_half_mirror row_mask:0xf bank_mask:0x5 bound_ctrl:1
	v_pk_fma_f32 v[6:7], v[2:3], v[86:87], v[10:11]
	v_add_f32_dpp v18, v18, v18 row_half_mirror row_mask:0xf bank_mask:0xf bound_ctrl:1
	v_add_f32_dpp v200, v200, v200 row_half_mirror row_mask:0xf bank_mask:0xa bound_ctrl:1
	v_add_f32_dpp v200, v194, v194 row_half_mirror row_mask:0xf bank_mask:0x5 bound_ctrl:1
	v_add_f32_dpp v18, v18, v18 row_ror:8 row_mask:0xf bank_mask:0xf bound_ctrl:1
	v_pk_fma_f32 v[0:1], v[92:93], v[18:19], v[4:5] op_sel_hi:[1,0,1] neg_lo:[1,0,0] neg_hi:[1,0,0]
	v_pk_fma_f32 v[2:3], v[94:95], v[18:19], v[6:7] op_sel_hi:[1,0,1] neg_lo:[1,0,0] neg_hi:[1,0,0]
	s_waitcnt lgkmcnt(6)
	v_pk_mul_f32 v[8:9], v[118:119], v[126:127] op_sel_hi:[1,0]
	v_pk_mul_f32 v[10:11], v[120:121], v[126:127] op_sel_hi:[1,0]
	ds_read_b128 v[74:77], v139 offset:7488
	ds_read_b32 v82, v140 offset:6720
	ds_read_b128 v[66:69], v139 offset:6976
	ds_read_b128 v[62:65], v139 offset:6720
	ds_read_b128 v[70:73], v139 offset:7232
	ds_read_b128 v[78:81], v139 offset:7744
	v_pk_mul_f32 v[16:17], v[0:1], v[110:111]
	v_pk_fma_f32 v[16:17], v[2:3], v[112:113], v[16:17]
	v_add_f32_e32 v18, v16, v17
	v_pk_mul_f32 v[20:21], v[0:1], v[100:101]
	v_pk_fma_f32 v[4:5], v[0:1], v[106:107], v[8:9]
	v_add_f32_dpp v18, v18, v18 quad_perm:[1,0,3,2] row_mask:0xf bank_mask:0xf bound_ctrl:1
	v_pk_fma_f32 v[20:21], v[2:3], v[102:103], v[20:21]
	v_add_f32_e32 v14, v20, v21
	v_add_f32_dpp v18, v18, v18 quad_perm:[2,3,0,1] row_mask:0xf bank_mask:0xf bound_ctrl:1
	v_add_f32_dpp v201, v201, v201 row_half_mirror row_mask:0xf bank_mask:0xa bound_ctrl:1
	v_pk_fma_f32 v[6:7], v[2:3], v[108:109], v[10:11]
	v_add_f32_dpp v18, v18, v18 row_half_mirror row_mask:0xf bank_mask:0xf bound_ctrl:1
	v_add_f32_dpp v201, v195, v195 row_half_mirror row_mask:0xf bank_mask:0x5 bound_ctrl:1
	v_cndmask_b32_e64 v22, v196, v200, s[36:37]
	v_add_f32_dpp v18, v18, v18 row_ror:8 row_mask:0xf bank_mask:0xf bound_ctrl:1
	v_pk_fma_f32 v[0:1], v[114:115], v[18:19], v[4:5] op_sel_hi:[1,0,1] neg_lo:[1,0,0] neg_hi:[1,0,0]
	v_pk_fma_f32 v[2:3], v[116:117], v[18:19], v[6:7] op_sel_hi:[1,0,1] neg_lo:[1,0,0] neg_hi:[1,0,0]
	s_waitcnt lgkmcnt(6)
	v_pk_mul_f32 v[8:9], v[52:53], v[60:61] op_sel_hi:[1,0]
	v_pk_mul_f32 v[10:11], v[54:55], v[60:61] op_sel_hi:[1,0]
	ds_read_b128 v[96:99], v139 offset:8832
	ds_read_b32 v104, v140 offset:8064
	ds_read_b128 v[88:91], v139 offset:8320
	ds_read_b128 v[84:87], v139 offset:8064
	ds_read_b128 v[92:95], v139 offset:8576
	ds_read_b128 v[100:103], v139 offset:9088
	v_pk_mul_f32 v[16:17], v[0:1], v[44:45]
	v_pk_fma_f32 v[16:17], v[2:3], v[46:47], v[16:17]
	v_add_f32_e32 v18, v16, v17
	v_pk_mul_f32 v[20:21], v[0:1], v[122:123]
	v_pk_fma_f32 v[4:5], v[0:1], v[40:41], v[8:9]
	v_add_f32_dpp v18, v18, v18 quad_perm:[1,0,3,2] row_mask:0xf bank_mask:0xf bound_ctrl:1
	v_pk_fma_f32 v[20:21], v[2:3], v[124:125], v[20:21]
	v_add_f32_e32 v15, v20, v21
	v_add_f32_dpp v18, v18, v18 quad_perm:[2,3,0,1] row_mask:0xf bank_mask:0xf bound_ctrl:1
	v_cndmask_b32_e64 v202, v200, v196, s[36:37]
	v_pk_fma_f32 v[6:7], v[2:3], v[42:43], v[10:11]
	v_add_f32_dpp v18, v18, v18 row_half_mirror row_mask:0xf bank_mask:0xf bound_ctrl:1
	v_add_f32_dpp v200, v202, v22 quad_perm:[2,3,0,1] row_mask:0xf bank_mask:0xf bound_ctrl:1
	v_cndmask_b32_e64 v203, v197, v201, s[36:37]
	v_add_f32_dpp v18, v18, v18 row_ror:8 row_mask:0xf bank_mask:0xf bound_ctrl:1
	v_pk_fma_f32 v[0:1], v[48:49], v[18:19], v[4:5] op_sel_hi:[1,0,1] neg_lo:[1,0,0] neg_hi:[1,0,0]
	v_pk_fma_f32 v[2:3], v[50:51], v[18:19], v[6:7] op_sel_hi:[1,0,1] neg_lo:[1,0,0] neg_hi:[1,0,0]
	s_waitcnt lgkmcnt(6)
	v_pk_mul_f32 v[8:9], v[74:75], v[82:83] op_sel_hi:[1,0]
	v_pk_mul_f32 v[10:11], v[76:77], v[82:83] op_sel_hi:[1,0]
	ds_read_b128 v[118:121], v139 offset:10176
	ds_read_b32 v126, v140 offset:9408
	ds_read_b128 v[110:113], v139 offset:9664
	ds_read_b128 v[106:109], v139 offset:9408
	ds_read_b128 v[114:117], v139 offset:9920
	ds_read_b128 v[122:125], v139 offset:10432
	v_pk_mul_f32 v[16:17], v[0:1], v[66:67]
	v_pk_fma_f32 v[16:17], v[2:3], v[68:69], v[16:17]
	v_add_f32_e32 v18, v16, v17
	v_pk_mul_f32 v[20:21], v[0:1], v[56:57]
	v_pk_fma_f32 v[4:5], v[0:1], v[62:63], v[8:9]
	v_add_f32_dpp v18, v18, v18 quad_perm:[1,0,3,2] row_mask:0xf bank_mask:0xf bound_ctrl:1
	v_pk_fma_f32 v[20:21], v[2:3], v[58:59], v[20:21]
	v_add_f32_e32 v188, v20, v21
	v_add_f32_dpp v18, v18, v18 quad_perm:[2,3,0,1] row_mask:0xf bank_mask:0xf bound_ctrl:1
	v_cndmask_b32_e64 v202, v201, v197, s[36:37]
	v_pk_fma_f32 v[6:7], v[2:3], v[64:65], v[10:11]
	v_add_f32_dpp v18, v18, v18 row_half_mirror row_mask:0xf bank_mask:0xf bound_ctrl:1
	v_add_f32_dpp v201, v202, v203 quad_perm:[2,3,0,1] row_mask:0xf bank_mask:0xf bound_ctrl:1
	v_cndmask_b32_e64 v22, v200, v201, s[38:39]
	v_add_f32_dpp v18, v18, v18 row_ror:8 row_mask:0xf bank_mask:0xf bound_ctrl:1
	v_pk_fma_f32 v[0:1], v[70:71], v[18:19], v[4:5] op_sel_hi:[1,0,1] neg_lo:[1,0,0] neg_hi:[1,0,0]
	v_pk_fma_f32 v[2:3], v[72:73], v[18:19], v[6:7] op_sel_hi:[1,0,1] neg_lo:[1,0,0] neg_hi:[1,0,0]
	s_waitcnt lgkmcnt(6)
	v_pk_mul_f32 v[8:9], v[96:97], v[104:105] op_sel_hi:[1,0]
	v_pk_mul_f32 v[10:11], v[98:99], v[104:105] op_sel_hi:[1,0]
	ds_read_b128 v[52:55], v139 offset:11520
	ds_read_b32 v60, v140 offset:10752
	ds_read_b128 v[44:47], v139 offset:11008
	ds_read_b128 v[40:43], v139 offset:10752
	ds_read_b128 v[48:51], v139 offset:11264
	ds_read_b128 v[56:59], v139 offset:11776
	v_pk_mul_f32 v[16:17], v[0:1], v[88:89]
	v_pk_fma_f32 v[16:17], v[2:3], v[90:91], v[16:17]
	v_add_f32_e32 v18, v16, v17
	v_pk_mul_f32 v[20:21], v[0:1], v[78:79]
	v_pk_fma_f32 v[4:5], v[0:1], v[84:85], v[8:9]
	v_add_f32_dpp v18, v18, v18 quad_perm:[1,0,3,2] row_mask:0xf bank_mask:0xf bound_ctrl:1
	v_pk_fma_f32 v[20:21], v[2:3], v[80:81], v[20:21]
	v_add_f32_e32 v189, v20, v21
	v_add_f32_dpp v18, v18, v18 quad_perm:[2,3,0,1] row_mask:0xf bank_mask:0xf bound_ctrl:1
	v_cndmask_b32_e64 v202, v201, v200, s[38:39]
	v_pk_fma_f32 v[6:7], v[2:3], v[86:87], v[10:11]
	v_add_f32_dpp v18, v18, v18 row_half_mirror row_mask:0xf bank_mask:0xf bound_ctrl:1
	v_add_f32_dpp v23, v202, v22 quad_perm:[1,0,3,2] row_mask:0xf bank_mask:0xf bound_ctrl:1
	s_nop 0
	v_add_f32_dpp v18, v18, v18 row_ror:8 row_mask:0xf bank_mask:0xf bound_ctrl:1
	v_pk_fma_f32 v[0:1], v[92:93], v[18:19], v[4:5] op_sel_hi:[1,0,1] neg_lo:[1,0,0] neg_hi:[1,0,0]
	v_pk_fma_f32 v[2:3], v[94:95], v[18:19], v[6:7] op_sel_hi:[1,0,1] neg_lo:[1,0,0] neg_hi:[1,0,0]
	s_waitcnt lgkmcnt(6)
	v_pk_mul_f32 v[8:9], v[118:119], v[126:127] op_sel_hi:[1,0]
	v_pk_mul_f32 v[10:11], v[120:121], v[126:127] op_sel_hi:[1,0]
	s_cmp_eq_u32 s4, 0
	s_cbranch_scc1 .Lscan_noy0
	global_store_dword v138, v23, s[96:97]
	v_add_u32_e32 v138, s90, v138
.Lscan_noy0:
	ds_read_b128 v[74:77], v139 offset:12864
	ds_read_b32 v82, v140 offset:12096
	ds_read_b128 v[66:69], v139 offset:12352
	ds_read_b128 v[62:65], v139 offset:12096
	ds_read_b128 v[70:73], v139 offset:12608
	ds_read_b128 v[78:81], v139 offset:13120
	v_pk_mul_f32 v[16:17], v[0:1], v[110:111]
	v_pk_fma_f32 v[16:17], v[2:3], v[112:113], v[16:17]
	v_add_f32_e32 v18, v16, v17
	v_pk_mul_f32 v[20:21], v[0:1], v[100:101]
	v_pk_fma_f32 v[4:5], v[0:1], v[106:107], v[8:9]
	v_add_f32_dpp v18, v18, v18 quad_perm:[1,0,3,2] row_mask:0xf bank_mask:0xf bound_ctrl:1
	v_pk_fma_f32 v[20:21], v[2:3], v[102:103], v[20:21]
	v_add_f32_e32 v190, v20, v21
	v_add_f32_dpp v18, v18, v18 quad_perm:[2,3,0,1] row_mask:0xf bank_mask:0xf bound_ctrl:1
	s_nop 0
	v_pk_fma_f32 v[6:7], v[2:3], v[108:109], v[10:11]
	v_add_f32_dpp v18, v18, v18 row_half_mirror row_mask:0xf bank_mask:0xf bound_ctrl:1
	s_nop 0
	s_nop 0
	v_add_f32_dpp v18, v18, v18 row_ror:8 row_mask:0xf bank_mask:0xf bound_ctrl:1
	v_pk_fma_f32 v[0:1], v[114:115], v[18:19], v[4:5] op_sel_hi:[1,0,1] neg_lo:[1,0,0] neg_hi:[1,0,0]
	v_pk_fma_f32 v[2:3], v[116:117], v[18:19], v[6:7] op_sel_hi:[1,0,1] neg_lo:[1,0,0] neg_hi:[1,0,0]
	s_waitcnt lgkmcnt(6)
	v_pk_mul_f32 v[8:9], v[52:53], v[60:61] op_sel_hi:[1,0]
	v_pk_mul_f32 v[10:11], v[54:55], v[60:61] op_sel_hi:[1,0]
	ds_read_b128 v[96:99], v139 offset:14208
	ds_read_b32 v104, v140 offset:13440
	ds_read_b128 v[88:91], v139 offset:13696
	ds_read_b128 v[84:87], v139 offset:13440
	ds_read_b128 v[92:95], v139 offset:13952
	ds_read_b128 v[100:103], v139 offset:14464
	v_pk_mul_f32 v[16:17], v[0:1], v[44:45]
	v_pk_fma_f32 v[16:17], v[2:3], v[46:47], v[16:17]
	v_add_f32_e32 v18, v16, v17
	v_pk_mul_f32 v[20:21], v[0:1], v[122:123]
	v_pk_fma_f32 v[4:5], v[0:1], v[40:41], v[8:9]
	v_add_f32_dpp v18, v18, v18 quad_perm:[1,0,3,2] row_mask:0xf bank_mask:0xf bound_ctrl:1
	v_pk_fma_f32 v[20:21], v[2:3], v[124:125], v[20:21]
	v_add_f32_e32 v191, v20, v21
	v_add_f32_dpp v18, v18, v18 quad_perm:[2,3,0,1] row_mask:0xf bank_mask:0xf bound_ctrl:1
	s_nop 0
	v_pk_fma_f32 v[6:7], v[2:3], v[42:43], v[10:11]
	v_add_f32_dpp v18, v18, v18 row_half_mirror row_mask:0xf bank_mask:0xf bound_ctrl:1
	s_nop 0
	s_nop 0
	v_add_f32_dpp v18, v18, v18 row_ror:8 row_mask:0xf bank_mask:0xf bound_ctrl:1
	v_pk_fma_f32 v[0:1], v[48:49], v[18:19], v[4:5] op_sel_hi:[1,0,1] neg_lo:[1,0,0] neg_hi:[1,0,0]
	v_pk_fma_f32 v[2:3], v[50:51], v[18:19], v[6:7] op_sel_hi:[1,0,1] neg_lo:[1,0,0] neg_hi:[1,0,0]
	s_waitcnt lgkmcnt(6)
	v_pk_mul_f32 v[8:9], v[74:75], v[82:83] op_sel_hi:[1,0]
	v_pk_mul_f32 v[10:11], v[76:77], v[82:83] op_sel_hi:[1,0]
	ds_read_b128 v[118:121], v139 offset:15552
	ds_read_b32 v126, v140 offset:14784
	ds_read_b128 v[110:113], v139 offset:15040
	ds_read_b128 v[106:109], v139 offset:14784
	ds_read_b128 v[114:117], v139 offset:15296
	ds_read_b128 v[122:125], v139 offset:15808
	v_pk_mul_f32 v[16:17], v[0:1], v[66:67]
	v_pk_fma_f32 v[16:17], v[2:3], v[68:69], v[16:17]
	v_add_f32_e32 v18, v16, v17
	v_pk_mul_f32 v[20:21], v[0:1], v[56:57]
	v_pk_fma_f32 v[4:5], v[0:1], v[62:63], v[8:9]
	v_add_f32_dpp v18, v18, v18 quad_perm:[1,0,3,2] row_mask:0xf bank_mask:0xf bound_ctrl:1
	v_pk_fma_f32 v[20:21], v[2:3], v[58:59], v[20:21]
	v_add_f32_e32 v192, v20, v21
	v_add_f32_dpp v18, v18, v18 quad_perm:[2,3,0,1] row_mask:0xf bank_mask:0xf bound_ctrl:1
	s_nop 0
	v_pk_fma_f32 v[6:7], v[2:3], v[64:65], v[10:11]
	v_add_f32_dpp v18, v18, v18 row_half_mirror row_mask:0xf bank_mask:0xf bound_ctrl:1
	v_add_f32_dpp v192, v192, v192 row_ror:8 row_mask:0xf bank_mask:0xc bound_ctrl:1
	v_add_f32_dpp v192, v12, v12 row_ror:8 row_mask:0xf bank_mask:0x3 bound_ctrl:1
	v_add_f32_dpp v18, v18, v18 row_ror:8 row_mask:0xf bank_mask:0xf bound_ctrl:1
	v_pk_fma_f32 v[0:1], v[70:71], v[18:19], v[4:5] op_sel_hi:[1,0,1] neg_lo:[1,0,0] neg_hi:[1,0,0]
	v_pk_fma_f32 v[2:3], v[72:73], v[18:19], v[6:7] op_sel_hi:[1,0,1] neg_lo:[1,0,0] neg_hi:[1,0,0]
	s_waitcnt lgkmcnt(6)
	v_pk_mul_f32 v[8:9], v[96:97], v[104:105] op_sel_hi:[1,0]
	v_pk_mul_f32 v[10:11], v[98:99], v[104:105] op_sel_hi:[1,0]
	ds_read_b128 v[52:55], v139 offset:16896
	ds_read_b32 v60, v140 offset:16128
	ds_read_b128 v[44:47], v139 offset:16384
	ds_read_b128 v[40:43], v139 offset:16128
	ds_read_b128 v[48:51], v139 offset:16640
	ds_read_b128 v[56:59], v139 offset:17152
	v_pk_mul_f32 v[16:17], v[0:1], v[88:89]
	v_pk_fma_f32 v[16:17], v[2:3], v[90:91], v[16:17]
	v_add_f32_e32 v18, v16, v17
	v_pk_mul_f32 v[20:21], v[0:1], v[78:79]
	v_pk_fma_f32 v[4:5], v[0:1], v[84:85], v[8:9]
	v_add_f32_dpp v18, v18, v18 quad_perm:[1,0,3,2] row_mask:0xf bank_mask:0xf bound_ctrl:1
	v_pk_fma_f32 v[20:21], v[2:3], v[80:81], v[20:21]
	v_add_f32_e32 v193, v20, v21
	v_add_f32_dpp v18, v18, v18 quad_perm:[2,3,0,1] row_mask:0xf bank_mask:0xf bound_ctrl:1
	s_nop 0
	v_pk_fma_f32 v[6:7], v[2:3], v[86:87], v[10:11]
	v_add_f32_dpp v18, v18, v18 row_half_mirror row_mask:0xf bank_mask:0xf bound_ctrl:1
	v_add_f32_dpp v193, v193, v193 row_ror:8 row_mask:0xf bank_mask:0xc bound_ctrl:1
	v_add_f32_dpp v193, v13, v13 row_ror:8 row_mask:0xf bank_mask:0x3 bound_ctrl:1
	v_add_f32_dpp v18, v18, v18 row_ror:8 row_mask:0xf bank_mask:0xf bound_ctrl:1
	v_pk_fma_f32 v[0:1], v[92:93], v[18:19], v[4:5] op_sel_hi:[1,0,1] neg_lo:[1,0,0] neg_hi:[1,0,0]
	v_pk_fma_f32 v[2:3], v[94:95], v[18:19], v[6:7] op_sel_hi:[1,0,1] neg_lo:[1,0,0] neg_hi:[1,0,0]
	s_waitcnt lgkmcnt(6)
	v_pk_mul_f32 v[8:9], v[118:119], v[126:127] op_sel_hi:[1,0]
	v_pk_mul_f32 v[10:11], v[120:121], v[126:127] op_sel_hi:[1,0]
	s_add_i32 s0, s4, 2
	s_cmp_lt_u32 s0, s5
	s_cbranch_scc1 .Lscan_w6_0
	s_waitcnt vmcnt(0)
	s_branch .Lscan_wd_0

.Lscan_wd_0:
	ds_write_b128 v143, v[146:149]
	ds_write_b128 v143, v[150:153] offset:256
	ds_write_b128 v143, v[154:157] offset:512
	ds_write_b128 v143, v[158:161] offset:768
	ds_write_b128 v143, v[162:165] offset:1024
	ds_write_b32 v35, v166
	ds_read_b128 v[74:77], v139 offset:18240
	ds_read_b32 v82, v140 offset:17472
	ds_read_b128 v[66:69], v139 offset:17728
	ds_read_b128 v[62:65], v139 offset:17472
	ds_read_b128 v[70:73], v139 offset:17984
	ds_read_b128 v[78:81], v139 offset:18496
	v_pk_mul_f32 v[16:17], v[0:1], v[110:111]
	v_pk_fma_f32 v[16:17], v[2:3], v[112:113], v[16:17]
	v_add_f32_e32 v18, v16, v17
	v_pk_mul_f32 v[20:21], v[0:1], v[100:101]
	v_pk_fma_f32 v[4:5], v[0:1], v[106:107], v[8:9]
	v_add_f32_dpp v18, v18, v18 quad_perm:[1,0,3,2] row_mask:0xf bank_mask:0xf bound_ctrl:1
	v_pk_fma_f32 v[20:21], v[2:3], v[102:103], v[20:21]
	v_add_f32_e32 v194, v20, v21
	v_add_f32_dpp v18, v18, v18 quad_perm:[2,3,0,1] row_mask:0xf bank_mask:0xf bound_ctrl:1
	s_nop 0
	v_pk_fma_f32 v[6:7], v[2:3], v[108:109], v[10:11]
	v_add_f32_dpp v18, v18, v18 row_half_mirror row_mask:0xf bank_mask:0xf bound_ctrl:1
	v_add_f32_dpp v194, v194, v194 row_ror:8 row_mask:0xf bank_mask:0xc bound_ctrl:1
	v_add_f32_dpp v194, v14, v14 row_ror:8 row_mask:0xf bank_mask:0x3 bound_ctrl:1
	v_add_f32_dpp v18, v18, v18 row_ror:8 row_mask:0xf bank_mask:0xf bound_ctrl:1
	v_pk_fma_f32 v[0:1], v[114:115], v[18:19], v[4:5] op_sel_hi:[1,0,1] neg_lo:[1,0,0] neg_hi:[1,0,0]
	v_pk_fma_f32 v[2:3], v[116:117], v[18:19], v[6:7] op_sel_hi:[1,0,1] neg_lo:[1,0,0] neg_hi:[1,0,0]
	s_waitcnt lgkmcnt(6)
	v_pk_mul_f32 v[8:9], v[52:53], v[60:61] op_sel_hi:[1,0]
	v_pk_mul_f32 v[10:11], v[54:55], v[60:61] op_sel_hi:[1,0]
	ds_read_b128 v[96:99], v139 offset:19584
	ds_read_b32 v104, v140 offset:18816
	ds_read_b128 v[88:91], v139 offset:19072
	ds_read_b128 v[84:87], v139 offset:18816
	ds_read_b128 v[92:95], v139 offset:19328
	ds_read_b128 v[100:103], v139 offset:19840
	v_pk_mul_f32 v[16:17], v[0:1], v[44:45]
	v_pk_fma_f32 v[16:17], v[2:3], v[46:47], v[16:17]
	v_add_f32_e32 v18, v16, v17
	v_pk_mul_f32 v[20:21], v[0:1], v[122:123]
	v_pk_fma_f32 v[4:5], v[0:1], v[40:41], v[8:9]
	v_add_f32_dpp v18, v18, v18 quad_perm:[1,0,3,2] row_mask:0xf bank_mask:0xf bound_ctrl:1
	v_pk_fma_f32 v[20:21], v[2:3], v[124:125], v[20:21]
	v_add_f32_e32 v195, v20, v21
	v_add_f32_dpp v18, v18, v18 quad_perm:[2,3,0,1] row_mask:0xf bank_mask:0xf bound_ctrl:1
	s_nop 0
	v_pk_fma_f32 v[6:7], v[2:3], v[42:43], v[10:11]
	v_add_f32_dpp v18, v18, v18 row_half_mirror row_mask:0xf bank_mask:0xf bound_ctrl:1
	v_add_f32_dpp v195, v195, v195 row_ror:8 row_mask:0xf bank_mask:0xc bound_ctrl:1
	v_add_f32_dpp v195, v15, v15 row_ror:8 row_mask:0xf bank_mask:0x3 bound_ctrl:1
	v_add_f32_dpp v18, v18, v18 row_ror:8 row_mask:0xf bank_mask:0xf bound_ctrl:1
	v_pk_fma_f32 v[0:1], v[48:49], v[18:19], v[4:5] op_sel_hi:[1,0,1] neg_lo:[1,0,0] neg_hi:[1,0,0]
	v_pk_fma_f32 v[2:3], v[50:51], v[18:19], v[6:7] op_sel_hi:[1,0,1] neg_lo:[1,0,0] neg_hi:[1,0,0]
	s_waitcnt lgkmcnt(6)
	s_barrier
	s_add_i32 s0, s4, 3
	s_cmp_lt_u32 s0, s5
	s_cbranch_scc0 .Lscan_nold0
	s_mul_i32 s92, s0, s90
	v_add_u32_e32 v132, s92, v28
	v_add_u32_e32 v133, s92, v29
	v_add_u32_e32 v134, s92, v30
	v_add_u32_e32 v135, s92, v31
	v_add_u32_e32 v136, s92, v32
	v_add_u32_e32 v137, s92, v33
	global_load_dwordx4 v[146:149], v132, s[96:97]
	global_load_dwordx4 v[150:153], v133, s[96:97]
	global_load_dwordx4 v[154:157], v134, s[96:97]
	global_load_dwordx4 v[158:161], v135, s[96:97]
	global_load_dwordx4 v[162:165], v136, s[96:97]
	global_load_dword v166, v137, s[96:97]
.Lscan_nold0:
	v_pk_mul_f32 v[8:9], v[74:75], v[82:83] op_sel_hi:[1,0]
	v_pk_mul_f32 v[10:11], v[76:77], v[82:83] op_sel_hi:[1,0]
	ds_read_b128 v[118:121], v139 offset:20928
	ds_read_b32 v126, v140 offset:20160
	ds_read_b128 v[110:113], v139 offset:20416
	ds_read_b128 v[106:109], v139 offset:20160
	ds_read_b128 v[114:117], v139 offset:20672
	ds_read_b128 v[122:125], v139 offset:21184
	v_pk_mul_f32 v[16:17], v[0:1], v[66:67]
	v_pk_fma_f32 v[16:17], v[2:3], v[68:69], v[16:17]
	v_add_f32_e32 v18, v16, v17
	v_pk_mul_f32 v[20:21], v[0:1], v[56:57]
	v_pk_fma_f32 v[4:5], v[0:1], v[62:63], v[8:9]
	v_add_f32_dpp v18, v18, v18 quad_perm:[1,0,3,2] row_mask:0xf bank_mask:0xf bound_ctrl:1
	v_pk_fma_f32 v[20:21], v[2:3], v[58:59], v[20:21]
	v_add_f32_e32 v196, v20, v21
	v_add_f32_dpp v18, v18, v18 quad_perm:[2,3,0,1] row_mask:0xf bank_mask:0xf bound_ctrl:1
	s_nop 0
	v_pk_fma_f32 v[6:7], v[2:3], v[64:65], v[10:11]
	v_add_f32_dpp v18, v18, v18 row_half_mirror row_mask:0xf bank_mask:0xf bound_ctrl:1
	v_add_f32_dpp v196, v196, v196 row_ror:8 row_mask:0xf bank_mask:0xc bound_ctrl:1
	v_add_f32_dpp v196, v188, v188 row_ror:8 row_mask:0xf bank_mask:0x3 bound_ctrl:1
	v_add_f32_dpp v18, v18, v18 row_ror:8 row_mask:0xf bank_mask:0xf bound_ctrl:1
	v_pk_fma_f32 v[0:1], v[70:71], v[18:19], v[4:5] op_sel_hi:[1,0,1] neg_lo:[1,0,0] neg_hi:[1,0,0]
	v_pk_fma_f32 v[2:3], v[72:73], v[18:19], v[6:7] op_sel_hi:[1,0,1] neg_lo:[1,0,0] neg_hi:[1,0,0]
	s_waitcnt lgkmcnt(6)
	v_pk_mul_f32 v[8:9], v[96:97], v[104:105] op_sel_hi:[1,0]
	v_pk_mul_f32 v[10:11], v[98:99], v[104:105] op_sel_hi:[1,0]
	ds_read_b128 v[52:55], v141 offset:768
	ds_read_b32 v60, v142 offset:0
	ds_read_b128 v[44:47], v141 offset:256
	ds_read_b128 v[40:43], v141 offset:0
	ds_read_b128 v[48:51], v141 offset:512
	ds_read_b128 v[56:59], v141 offset:1024
	v_pk_mul_f32 v[16:17], v[0:1], v[88:89]
	v_pk_fma_f32 v[16:17], v[2:3], v[90:91], v[16:17]
	v_add_f32_e32 v18, v16, v17
	v_pk_mul_f32 v[20:21], v[0:1], v[78:79]
	v_pk_fma_f32 v[4:5], v[0:1], v[84:85], v[8:9]
	v_add_f32_dpp v18, v18, v18 quad_perm:[1,0,3,2] row_mask:0xf bank_mask:0xf bound_ctrl:1
	v_pk_fma_f32 v[20:21], v[2:3], v[80:81], v[20:21]
	v_add_f32_e32 v197, v20, v21
	v_add_f32_dpp v18, v18, v18 quad_perm:[2,3,0,1] row_mask:0xf bank_mask:0xf bound_ctrl:1
	s_nop 0
	v_pk_fma_f32 v[6:7], v[2:3], v[86:87], v[10:11]
	v_add_f32_dpp v18, v18, v18 row_half_mirror row_mask:0xf bank_mask:0xf bound_ctrl:1
	v_add_f32_dpp v197, v197, v197 row_ror:8 row_mask:0xf bank_mask:0xc bound_ctrl:1
	v_add_f32_dpp v197, v189, v189 row_ror:8 row_mask:0xf bank_mask:0x3 bound_ctrl:1
	v_add_f32_dpp v18, v18, v18 row_ror:8 row_mask:0xf bank_mask:0xf bound_ctrl:1
	v_pk_fma_f32 v[0:1], v[92:93], v[18:19], v[4:5] op_sel_hi:[1,0,1] neg_lo:[1,0,0] neg_hi:[1,0,0]
	v_pk_fma_f32 v[2:3], v[94:95], v[18:19], v[6:7] op_sel_hi:[1,0,1] neg_lo:[1,0,0] neg_hi:[1,0,0]
	s_waitcnt lgkmcnt(6)
	v_pk_mul_f32 v[8:9], v[118:119], v[126:127] op_sel_hi:[1,0]
	v_pk_mul_f32 v[10:11], v[120:121], v[126:127] op_sel_hi:[1,0]
	ds_read_b128 v[74:77], v141 offset:2112
	ds_read_b32 v82, v142 offset:1344
	ds_read_b128 v[66:69], v141 offset:1600
	ds_read_b128 v[62:65], v141 offset:1344
	ds_read_b128 v[70:73], v141 offset:1856
	ds_read_b128 v[78:81], v141 offset:2368
	v_pk_mul_f32 v[16:17], v[0:1], v[110:111]
	v_pk_fma_f32 v[16:17], v[2:3], v[112:113], v[16:17]
	v_add_f32_e32 v18, v16, v17
	v_pk_mul_f32 v[20:21], v[0:1], v[100:101]
	v_pk_fma_f32 v[4:5], v[0:1], v[106:107], v[8:9]
	v_add_f32_dpp v18, v18, v18 quad_perm:[1,0,3,2] row_mask:0xf bank_mask:0xf bound_ctrl:1
	v_pk_fma_f32 v[20:21], v[2:3], v[102:103], v[20:21]
	v_add_f32_e32 v200, v20, v21
	v_add_f32_dpp v18, v18, v18 quad_perm:[2,3,0,1] row_mask:0xf bank_mask:0xf bound_ctrl:1
	s_nop 0
	v_pk_fma_f32 v[6:7], v[2:3], v[108:109], v[10:11]
	v_add_f32_dpp v18, v18, v18 row_half_mirror row_mask:0xf bank_mask:0xf bound_ctrl:1
	v_add_f32_dpp v200, v200, v200 row_ror:8 row_mask:0xf bank_mask:0xc bound_ctrl:1
	v_add_f32_dpp v200, v190, v190 row_ror:8 row_mask:0xf bank_mask:0x3 bound_ctrl:1
	v_add_f32_dpp v18, v18, v18 row_ror:8 row_mask:0xf bank_mask:0xf bound_ctrl:1
	v_pk_fma_f32 v[0:1], v[114:115], v[18:19], v[4:5] op_sel_hi:[1,0,1] neg_lo:[1,0,0] neg_hi:[1,0,0]
	v_pk_fma_f32 v[2:3], v[116:117], v[18:19], v[6:7] op_sel_hi:[1,0,1] neg_lo:[1,0,0] neg_hi:[1,0,0]
	s_waitcnt lgkmcnt(6)
	v_pk_mul_f32 v[8:9], v[52:53], v[60:61] op_sel_hi:[1,0]
	v_pk_mul_f32 v[10:11], v[54:55], v[60:61] op_sel_hi:[1,0]
	s_add_i32 s4, s4, 1
	s_mov_b32 s0, s6
	s_mov_b32 s6, s7
	s_mov_b32 s7, s25
	s_mov_b32 s25, s0
	v_mov_b32_e32 v139, v141
	v_mov_b32_e32 v140, v142
	v_add_u32_e32 v141, s7, v24
	v_add_u32_e32 v142, s7, v25
	v_add_u32_e32 v143, s7, v26
	v_add_u32_e32 v35, s7, v27
	ds_read_b128 v[96:99], v139 offset:3456
	ds_read_b32 v104, v140 offset:2688
	ds_read_b128 v[88:91], v139 offset:2944
	ds_read_b128 v[84:87], v139 offset:2688
	ds_read_b128 v[92:95], v139 offset:3200
	ds_read_b128 v[100:103], v139 offset:3712
	v_pk_mul_f32 v[16:17], v[0:1], v[44:45]
	v_pk_fma_f32 v[16:17], v[2:3], v[46:47], v[16:17]
	v_add_f32_e32 v18, v16, v17
	v_pk_mul_f32 v[20:21], v[0:1], v[122:123]
	v_pk_fma_f32 v[4:5], v[0:1], v[40:41], v[8:9]
	v_add_f32_dpp v18, v18, v18 quad_perm:[1,0,3,2] row_mask:0xf bank_mask:0xf bound_ctrl:1
	v_pk_fma_f32 v[20:21], v[2:3], v[124:125], v[20:21]
	v_add_f32_e32 v201, v20, v21
	v_add_f32_dpp v18, v18, v18 quad_perm:[2,3,0,1] row_mask:0xf bank_mask:0xf bound_ctrl:1
	s_nop 0
	v_pk_fma_f32 v[6:7], v[2:3], v[42:43], v[10:11]
	v_add_f32_dpp v18, v18, v18 row_half_mirror row_mask:0xf bank_mask:0xf bound_ctrl:1
	v_add_f32_dpp v201, v201, v201 row_ror:8 row_mask:0xf bank_mask:0xc bound_ctrl:1
	v_add_f32_dpp v201, v191, v191 row_ror:8 row_mask:0xf bank_mask:0x3 bound_ctrl:1
	v_add_f32_dpp v18, v18, v18 row_ror:8 row_mask:0xf bank_mask:0xf bound_ctrl:1
	v_pk_fma_f32 v[0:1], v[48:49], v[18:19], v[4:5] op_sel_hi:[1,0,1] neg_lo:[1,0,0] neg_hi:[1,0,0]
	v_pk_fma_f32 v[2:3], v[50:51], v[18:19], v[6:7] op_sel_hi:[1,0,1] neg_lo:[1,0,0] neg_hi:[1,0,0]
	s_waitcnt lgkmcnt(6)
	v_pk_mul_f32 v[8:9], v[74:75], v[82:83] op_sel_hi:[1,0]
	v_pk_mul_f32 v[10:11], v[76:77], v[82:83] op_sel_hi:[1,0]
	ds_read_b128 v[118:121], v139 offset:4800
	ds_read_b32 v126, v140 offset:4032
	ds_read_b128 v[110:113], v139 offset:4288
	ds_read_b128 v[106:109], v139 offset:4032
	ds_read_b128 v[114:117], v139 offset:4544
	ds_read_b128 v[122:125], v139 offset:5056
	v_pk_mul_f32 v[16:17], v[0:1], v[66:67]
	v_pk_fma_f32 v[16:17], v[2:3], v[68:69], v[16:17]
	v_add_f32_e32 v18, v16, v17
	v_pk_mul_f32 v[20:21], v[0:1], v[56:57]
	v_pk_fma_f32 v[4:5], v[0:1], v[62:63], v[8:9]
	v_add_f32_dpp v18, v18, v18 quad_perm:[1,0,3,2] row_mask:0xf bank_mask:0xf bound_ctrl:1
	v_pk_fma_f32 v[20:21], v[2:3], v[58:59], v[20:21]
	v_add_f32_e32 v12, v20, v21
	v_add_f32_dpp v18, v18, v18 quad_perm:[2,3,0,1] row_mask:0xf bank_mask:0xf bound_ctrl:1
	v_add_f32_dpp v196, v196, v196 row_half_mirror row_mask:0xf bank_mask:0xa bound_ctrl:1
	v_pk_fma_f32 v[6:7], v[2:3], v[64:65], v[10:11]
	v_add_f32_dpp v18, v18, v18 row_half_mirror row_mask:0xf bank_mask:0xf bound_ctrl:1
	v_add_f32_dpp v196, v192, v192 row_half_mirror row_mask:0xf bank_mask:0x5 bound_ctrl:1
	v_add_f32_dpp v197, v197, v197 row_half_mirror row_mask:0xf bank_mask:0xa bound_ctrl:1
	v_add_f32_dpp v18, v18, v18 row_ror:8 row_mask:0xf bank_mask:0xf bound_ctrl:1
	v_pk_fma_f32 v[0:1], v[70:71], v[18:19], v[4:5] op_sel_hi:[1,0,1] neg_lo:[1,0,0] neg_hi:[1,0,0]
	v_pk_fma_f32 v[2:3], v[72:73], v[18:19], v[6:7] op_sel_hi:[1,0,1] neg_lo:[1,0,0] neg_hi:[1,0,0]
	s_waitcnt lgkmcnt(6)
	v_pk_mul_f32 v[8:9], v[96:97], v[104:105] op_sel_hi:[1,0]
	v_pk_mul_f32 v[10:11], v[98:99], v[104:105] op_sel_hi:[1,0]
	ds_read_b128 v[52:55], v139 offset:6144
	ds_read_b32 v60, v140 offset:5376
	ds_read_b128 v[44:47], v139 offset:5632
	ds_read_b128 v[40:43], v139 offset:5376
	ds_read_b128 v[48:51], v139 offset:5888
	ds_read_b128 v[56:59], v139 offset:6400
	v_pk_mul_f32 v[16:17], v[0:1], v[88:89]
	v_pk_fma_f32 v[16:17], v[2:3], v[90:91], v[16:17]
	v_add_f32_e32 v18, v16, v17
	v_pk_mul_f32 v[20:21], v[0:1], v[78:79]
	v_pk_fma_f32 v[4:5], v[0:1], v[84:85], v[8:9]
	v_add_f32_dpp v18, v18, v18 quad_perm:[1,0,3,2] row_mask:0xf bank_mask:0xf bound_ctrl:1
	v_pk_fma_f32 v[20:21], v[2:3], v[80:81], v[20:21]
	v_add_f32_e32 v13, v20, v21
	v_add_f32_dpp v18, v18, v18 quad_perm:[2,3,0,1] row_mask:0xf bank_mask:0xf bound_ctrl:1
	v_add_f32_dpp v197, v193, v193 row_half_mirror row_mask:0xf bank_mask:0x5 bound_ctrl:1
	v_pk_fma_f32 v[6:7], v[2:3], v[86:87], v[10:11]
	v_add_f32_dpp v18, v18, v18 row_half_mirror row_mask:0xf bank_mask:0xf bound_ctrl:1
	v_add_f32_dpp v200, v200, v200 row_half_mirror row_mask:0xf bank_mask:0xa bound_ctrl:1
	v_add_f32_dpp v200, v194, v194 row_half_mirror row_mask:0xf bank_mask:0x5 bound_ctrl:1
	v_add_f32_dpp v18, v18, v18 row_ror:8 row_mask:0xf bank_mask:0xf bound_ctrl:1
	v_pk_fma_f32 v[0:1], v[92:93], v[18:19], v[4:5] op_sel_hi:[1,0,1] neg_lo:[1,0,0] neg_hi:[1,0,0]
	v_pk_fma_f32 v[2:3], v[94:95], v[18:19], v[6:7] op_sel_hi:[1,0,1] neg_lo:[1,0,0] neg_hi:[1,0,0]
	s_waitcnt lgkmcnt(6)
	v_pk_mul_f32 v[8:9], v[118:119], v[126:127] op_sel_hi:[1,0]
	v_pk_mul_f32 v[10:11], v[120:121], v[126:127] op_sel_hi:[1,0]
	ds_read_b128 v[74:77], v139 offset:7488
	ds_read_b32 v82, v140 offset:6720
	ds_read_b128 v[66:69], v139 offset:6976
	ds_read_b128 v[62:65], v139 offset:6720
	ds_read_b128 v[70:73], v139 offset:7232
	ds_read_b128 v[78:81], v139 offset:7744
	v_pk_mul_f32 v[16:17], v[0:1], v[110:111]
	v_pk_fma_f32 v[16:17], v[2:3], v[112:113], v[16:17]
	v_add_f32_e32 v18, v16, v17
	v_pk_mul_f32 v[20:21], v[0:1], v[100:101]
	v_pk_fma_f32 v[4:5], v[0:1], v[106:107], v[8:9]
	v_add_f32_dpp v18, v18, v18 quad_perm:[1,0,3,2] row_mask:0xf bank_mask:0xf bound_ctrl:1
	v_pk_fma_f32 v[20:21], v[2:3], v[102:103], v[20:21]
	v_add_f32_e32 v14, v20, v21
	v_add_f32_dpp v18, v18, v18 quad_perm:[2,3,0,1] row_mask:0xf bank_mask:0xf bound_ctrl:1
	v_add_f32_dpp v201, v201, v201 row_half_mirror row_mask:0xf bank_mask:0xa bound_ctrl:1
	v_pk_fma_f32 v[6:7], v[2:3], v[108:109], v[10:11]
	v_add_f32_dpp v18, v18, v18 row_half_mirror row_mask:0xf bank_mask:0xf bound_ctrl:1
	v_add_f32_dpp v201, v195, v195 row_half_mirror row_mask:0xf bank_mask:0x5 bound_ctrl:1
	v_cndmask_b32_e64 v22, v196, v200, s[36:37]
	v_add_f32_dpp v18, v18, v18 row_ror:8 row_mask:0xf bank_mask:0xf bound_ctrl:1
	v_pk_fma_f32 v[0:1], v[114:115], v[18:19], v[4:5] op_sel_hi:[1,0,1] neg_lo:[1,0,0] neg_hi:[1,0,0]
	v_pk_fma_f32 v[2:3], v[116:117], v[18:19], v[6:7] op_sel_hi:[1,0,1] neg_lo:[1,0,0] neg_hi:[1,0,0]
	s_waitcnt lgkmcnt(6)
	v_pk_mul_f32 v[8:9], v[52:53], v[60:61] op_sel_hi:[1,0]
	v_pk_mul_f32 v[10:11], v[54:55], v[60:61] op_sel_hi:[1,0]
	ds_read_b128 v[96:99], v139 offset:8832
	ds_read_b32 v104, v140 offset:8064
	ds_read_b128 v[88:91], v139 offset:8320
	ds_read_b128 v[84:87], v139 offset:8064
	ds_read_b128 v[92:95], v139 offset:8576
	ds_read_b128 v[100:103], v139 offset:9088
	v_pk_mul_f32 v[16:17], v[0:1], v[44:45]
	v_pk_fma_f32 v[16:17], v[2:3], v[46:47], v[16:17]
	v_add_f32_e32 v18, v16, v17
	v_pk_mul_f32 v[20:21], v[0:1], v[122:123]
	v_pk_fma_f32 v[4:5], v[0:1], v[40:41], v[8:9]
	v_add_f32_dpp v18, v18, v18 quad_perm:[1,0,3,2] row_mask:0xf bank_mask:0xf bound_ctrl:1
	v_pk_fma_f32 v[20:21], v[2:3], v[124:125], v[20:21]
	v_add_f32_e32 v15, v20, v21
	v_add_f32_dpp v18, v18, v18 quad_perm:[2,3,0,1] row_mask:0xf bank_mask:0xf bound_ctrl:1
	v_cndmask_b32_e64 v202, v200, v196, s[36:37]
	v_pk_fma_f32 v[6:7], v[2:3], v[42:43], v[10:11]
	v_add_f32_dpp v18, v18, v18 row_half_mirror row_mask:0xf bank_mask:0xf bound_ctrl:1
	v_add_f32_dpp v200, v202, v22 quad_perm:[2,3,0,1] row_mask:0xf bank_mask:0xf bound_ctrl:1
	v_cndmask_b32_e64 v203, v197, v201, s[36:37]
	v_add_f32_dpp v18, v18, v18 row_ror:8 row_mask:0xf bank_mask:0xf bound_ctrl:1
	v_pk_fma_f32 v[0:1], v[48:49], v[18:19], v[4:5] op_sel_hi:[1,0,1] neg_lo:[1,0,0] neg_hi:[1,0,0]
	v_pk_fma_f32 v[2:3], v[50:51], v[18:19], v[6:7] op_sel_hi:[1,0,1] neg_lo:[1,0,0] neg_hi:[1,0,0]
	s_waitcnt lgkmcnt(6)
	v_pk_mul_f32 v[8:9], v[74:75], v[82:83] op_sel_hi:[1,0]
	v_pk_mul_f32 v[10:11], v[76:77], v[82:83] op_sel_hi:[1,0]
	ds_read_b128 v[118:121], v139 offset:10176
	ds_read_b32 v126, v140 offset:9408
	ds_read_b128 v[110:113], v139 offset:9664
	ds_read_b128 v[106:109], v139 offset:9408
	ds_read_b128 v[114:117], v139 offset:9920
	ds_read_b128 v[122:125], v139 offset:10432
	v_pk_mul_f32 v[16:17], v[0:1], v[66:67]
	v_pk_fma_f32 v[16:17], v[2:3], v[68:69], v[16:17]
	v_add_f32_e32 v18, v16, v17
	v_pk_mul_f32 v[20:21], v[0:1], v[56:57]
	v_pk_fma_f32 v[4:5], v[0:1], v[62:63], v[8:9]
	v_add_f32_dpp v18, v18, v18 quad_perm:[1,0,3,2] row_mask:0xf bank_mask:0xf bound_ctrl:1
	v_pk_fma_f32 v[20:21], v[2:3], v[58:59], v[20:21]
	v_add_f32_e32 v188, v20, v21
	v_add_f32_dpp v18, v18, v18 quad_perm:[2,3,0,1] row_mask:0xf bank_mask:0xf bound_ctrl:1
	v_cndmask_b32_e64 v202, v201, v197, s[36:37]
	v_pk_fma_f32 v[6:7], v[2:3], v[64:65], v[10:11]
	v_add_f32_dpp v18, v18, v18 row_half_mirror row_mask:0xf bank_mask:0xf bound_ctrl:1
	v_add_f32_dpp v201, v202, v203 quad_perm:[2,3,0,1] row_mask:0xf bank_mask:0xf bound_ctrl:1
	v_cndmask_b32_e64 v22, v200, v201, s[38:39]
	v_add_f32_dpp v18, v18, v18 row_ror:8 row_mask:0xf bank_mask:0xf bound_ctrl:1
	v_pk_fma_f32 v[0:1], v[70:71], v[18:19], v[4:5] op_sel_hi:[1,0,1] neg_lo:[1,0,0] neg_hi:[1,0,0]
	v_pk_fma_f32 v[2:3], v[72:73], v[18:19], v[6:7] op_sel_hi:[1,0,1] neg_lo:[1,0,0] neg_hi:[1,0,0]
	s_waitcnt lgkmcnt(6)
	v_pk_mul_f32 v[8:9], v[96:97], v[104:105] op_sel_hi:[1,0]
	v_pk_mul_f32 v[10:11], v[98:99], v[104:105] op_sel_hi:[1,0]
	ds_read_b128 v[52:55], v139 offset:11520
	ds_read_b32 v60, v140 offset:10752
	ds_read_b128 v[44:47], v139 offset:11008
	ds_read_b128 v[40:43], v139 offset:10752
	ds_read_b128 v[48:51], v139 offset:11264
	ds_read_b128 v[56:59], v139 offset:11776
	v_pk_mul_f32 v[16:17], v[0:1], v[88:89]
	v_pk_fma_f32 v[16:17], v[2:3], v[90:91], v[16:17]
	v_add_f32_e32 v18, v16, v17
	v_pk_mul_f32 v[20:21], v[0:1], v[78:79]
	v_pk_fma_f32 v[4:5], v[0:1], v[84:85], v[8:9]
	v_add_f32_dpp v18, v18, v18 quad_perm:[1,0,3,2] row_mask:0xf bank_mask:0xf bound_ctrl:1
	v_pk_fma_f32 v[20:21], v[2:3], v[80:81], v[20:21]
	v_add_f32_e32 v189, v20, v21
	v_add_f32_dpp v18, v18, v18 quad_perm:[2,3,0,1] row_mask:0xf bank_mask:0xf bound_ctrl:1
	v_cndmask_b32_e64 v202, v201, v200, s[38:39]
	v_pk_fma_f32 v[6:7], v[2:3], v[86:87], v[10:11]
	v_add_f32_dpp v18, v18, v18 row_half_mirror row_mask:0xf bank_mask:0xf bound_ctrl:1
	v_add_f32_dpp v23, v202, v22 quad_perm:[1,0,3,2] row_mask:0xf bank_mask:0xf bound_ctrl:1
	s_nop 0
	v_add_f32_dpp v18, v18, v18 row_ror:8 row_mask:0xf bank_mask:0xf bound_ctrl:1
	v_pk_fma_f32 v[0:1], v[92:93], v[18:19], v[4:5] op_sel_hi:[1,0,1] neg_lo:[1,0,0] neg_hi:[1,0,0]
	v_pk_fma_f32 v[2:3], v[94:95], v[18:19], v[6:7] op_sel_hi:[1,0,1] neg_lo:[1,0,0] neg_hi:[1,0,0]
	s_waitcnt lgkmcnt(6)
	v_pk_mul_f32 v[8:9], v[118:119], v[126:127] op_sel_hi:[1,0]
	v_pk_mul_f32 v[10:11], v[120:121], v[126:127] op_sel_hi:[1,0]
	s_cmp_eq_u32 s4, 0
	s_cbranch_scc1 .Lscan_noy1
	global_store_dword v138, v23, s[96:97]
	v_add_u32_e32 v138, s90, v138

.Lscan_wd_1:
	ds_write_b128 v143, v[168:171]
	ds_write_b128 v143, v[172:175] offset:256
	ds_write_b128 v143, v[176:179] offset:512
	ds_write_b128 v143, v[180:183] offset:768
	ds_write_b128 v143, v[184:187] offset:1024
	ds_write_b32 v35, v167
	ds_read_b128 v[74:77], v139 offset:18240
	ds_read_b32 v82, v140 offset:17472
	ds_read_b128 v[66:69], v139 offset:17728
	ds_read_b128 v[62:65], v139 offset:17472
	ds_read_b128 v[70:73], v139 offset:17984
	ds_read_b128 v[78:81], v139 offset:18496
	v_pk_mul_f32 v[16:17], v[0:1], v[110:111]
	v_pk_fma_f32 v[16:17], v[2:3], v[112:113], v[16:17]
	v_add_f32_e32 v18, v16, v17
	v_pk_mul_f32 v[20:21], v[0:1], v[100:101]
	v_pk_fma_f32 v[4:5], v[0:1], v[106:107], v[8:9]
	v_add_f32_dpp v18, v18, v18 quad_perm:[1,0,3,2] row_mask:0xf bank_mask:0xf bound_ctrl:1
	v_pk_fma_f32 v[20:21], v[2:3], v[102:103], v[20:21]
	v_add_f32_e32 v194, v20, v21
	v_add_f32_dpp v18, v18, v18 quad_perm:[2,3,0,1] row_mask:0xf bank_mask:0xf bound_ctrl:1
	s_nop 0
	v_pk_fma_f32 v[6:7], v[2:3], v[108:109], v[10:11]
	v_add_f32_dpp v18, v18, v18 row_half_mirror row_mask:0xf bank_mask:0xf bound_ctrl:1
	v_add_f32_dpp v194, v194, v194 row_ror:8 row_mask:0xf bank_mask:0xc bound_ctrl:1
	v_add_f32_dpp v194, v14, v14 row_ror:8 row_mask:0xf bank_mask:0x3 bound_ctrl:1
	v_add_f32_dpp v18, v18, v18 row_ror:8 row_mask:0xf bank_mask:0xf bound_ctrl:1
	v_pk_fma_f32 v[0:1], v[114:115], v[18:19], v[4:5] op_sel_hi:[1,0,1] neg_lo:[1,0,0] neg_hi:[1,0,0]
	v_pk_fma_f32 v[2:3], v[116:117], v[18:19], v[6:7] op_sel_hi:[1,0,1] neg_lo:[1,0,0] neg_hi:[1,0,0]
	s_waitcnt lgkmcnt(6)
	v_pk_mul_f32 v[8:9], v[52:53], v[60:61] op_sel_hi:[1,0]
	v_pk_mul_f32 v[10:11], v[54:55], v[60:61] op_sel_hi:[1,0]
	ds_read_b128 v[96:99], v139 offset:19584
	ds_read_b32 v104, v140 offset:18816
	ds_read_b128 v[88:91], v139 offset:19072
	ds_read_b128 v[84:87], v139 offset:18816
	ds_read_b128 v[92:95], v139 offset:19328
	ds_read_b128 v[100:103], v139 offset:19840
	v_pk_mul_f32 v[16:17], v[0:1], v[44:45]
	v_pk_fma_f32 v[16:17], v[2:3], v[46:47], v[16:17]
	v_add_f32_e32 v18, v16, v17
	v_pk_mul_f32 v[20:21], v[0:1], v[122:123]
	v_pk_fma_f32 v[4:5], v[0:1], v[40:41], v[8:9]
	v_add_f32_dpp v18, v18, v18 quad_perm:[1,0,3,2] row_mask:0xf bank_mask:0xf bound_ctrl:1
	v_pk_fma_f32 v[20:21], v[2:3], v[124:125], v[20:21]
	v_add_f32_e32 v195, v20, v21
	v_add_f32_dpp v18, v18, v18 quad_perm:[2,3,0,1] row_mask:0xf bank_mask:0xf bound_ctrl:1
	s_nop 0
	v_pk_fma_f32 v[6:7], v[2:3], v[42:43], v[10:11]
	v_add_f32_dpp v18, v18, v18 row_half_mirror row_mask:0xf bank_mask:0xf bound_ctrl:1
	v_add_f32_dpp v195, v195, v195 row_ror:8 row_mask:0xf bank_mask:0xc bound_ctrl:1
	v_add_f32_dpp v195, v15, v15 row_ror:8 row_mask:0xf bank_mask:0x3 bound_ctrl:1
	v_add_f32_dpp v18, v18, v18 row_ror:8 row_mask:0xf bank_mask:0xf bound_ctrl:1
	v_pk_fma_f32 v[0:1], v[48:49], v[18:19], v[4:5] op_sel_hi:[1,0,1] neg_lo:[1,0,0] neg_hi:[1,0,0]
	v_pk_fma_f32 v[2:3], v[50:51], v[18:19], v[6:7] op_sel_hi:[1,0,1] neg_lo:[1,0,0] neg_hi:[1,0,0]
	s_waitcnt lgkmcnt(6)
	s_barrier
	s_add_i32 s0, s4, 3
	s_cmp_lt_u32 s0, s5
	s_cbranch_scc0 .Lscan_nold1
	s_mul_i32 s92, s0, s90
	v_add_u32_e32 v132, s92, v28
	v_add_u32_e32 v133, s92, v29
	v_add_u32_e32 v134, s92, v30
	v_add_u32_e32 v135, s92, v31
	v_add_u32_e32 v136, s92, v32
	v_add_u32_e32 v137, s92, v33
	global_load_dwordx4 v[168:171], v132, s[96:97]
	global_load_dwordx4 v[172:175], v133, s[96:97]
	global_load_dwordx4 v[176:179], v134, s[96:97]
	global_load_dwordx4 v[180:183], v135, s[96:97]
	global_load_dwordx4 v[184:187], v136, s[96:97]
	global_load_dword v167, v137, s[96:97]
.Lscan_nold1:
	v_pk_mul_f32 v[8:9], v[74:75], v[82:83] op_sel_hi:[1,0]
	v_pk_mul_f32 v[10:11], v[76:77], v[82:83] op_sel_hi:[1,0]
	ds_read_b128 v[118:121], v139 offset:20928
	ds_read_b32 v126, v140 offset:20160
	ds_read_b128 v[110:113], v139 offset:20416
	ds_read_b128 v[106:109], v139 offset:20160
	ds_read_b128 v[114:117], v139 offset:20672
	ds_read_b128 v[122:125], v139 offset:21184
	v_pk_mul_f32 v[16:17], v[0:1], v[66:67]
	v_pk_fma_f32 v[16:17], v[2:3], v[68:69], v[16:17]
	v_add_f32_e32 v18, v16, v17
	v_pk_mul_f32 v[20:21], v[0:1], v[56:57]
	v_pk_fma_f32 v[4:5], v[0:1], v[62:63], v[8:9]
	v_add_f32_dpp v18, v18, v18 quad_perm:[1,0,3,2] row_mask:0xf bank_mask:0xf bound_ctrl:1
	v_pk_fma_f32 v[20:21], v[2:3], v[58:59], v[20:21]
	v_add_f32_e32 v196, v20, v21
	v_add_f32_dpp v18, v18, v18 quad_perm:[2,3,0,1] row_mask:0xf bank_mask:0xf bound_ctrl:1
	s_nop 0
	v_pk_fma_f32 v[6:7], v[2:3], v[64:65], v[10:11]
	v_add_f32_dpp v18, v18, v18 row_half_mirror row_mask:0xf bank_mask:0xf bound_ctrl:1
	v_add_f32_dpp v196, v196, v196 row_ror:8 row_mask:0xf bank_mask:0xc bound_ctrl:1
	v_add_f32_dpp v196, v188, v188 row_ror:8 row_mask:0xf bank_mask:0x3 bound_ctrl:1
	v_add_f32_dpp v18, v18, v18 row_ror:8 row_mask:0xf bank_mask:0xf bound_ctrl:1
	v_pk_fma_f32 v[0:1], v[70:71], v[18:19], v[4:5] op_sel_hi:[1,0,1] neg_lo:[1,0,0] neg_hi:[1,0,0]
	v_pk_fma_f32 v[2:3], v[72:73], v[18:19], v[6:7] op_sel_hi:[1,0,1] neg_lo:[1,0,0] neg_hi:[1,0,0]
	s_waitcnt lgkmcnt(6)
	v_pk_mul_f32 v[8:9], v[96:97], v[104:105] op_sel_hi:[1,0]
	v_pk_mul_f32 v[10:11], v[98:99], v[104:105] op_sel_hi:[1,0]
	ds_read_b128 v[52:55], v141 offset:768
	ds_read_b32 v60, v142 offset:0
	ds_read_b128 v[44:47], v141 offset:256
	ds_read_b128 v[40:43], v141 offset:0
	ds_read_b128 v[48:51], v141 offset:512
	ds_read_b128 v[56:59], v141 offset:1024
	v_pk_mul_f32 v[16:17], v[0:1], v[88:89]
	v_pk_fma_f32 v[16:17], v[2:3], v[90:91], v[16:17]
	v_add_f32_e32 v18, v16, v17
	v_pk_mul_f32 v[20:21], v[0:1], v[78:79]
	v_pk_fma_f32 v[4:5], v[0:1], v[84:85], v[8:9]
	v_add_f32_dpp v18, v18, v18 quad_perm:[1,0,3,2] row_mask:0xf bank_mask:0xf bound_ctrl:1
	v_pk_fma_f32 v[20:21], v[2:3], v[80:81], v[20:21]
	v_add_f32_e32 v197, v20, v21
	v_add_f32_dpp v18, v18, v18 quad_perm:[2,3,0,1] row_mask:0xf bank_mask:0xf bound_ctrl:1
	s_nop 0
	v_pk_fma_f32 v[6:7], v[2:3], v[86:87], v[10:11]
	v_add_f32_dpp v18, v18, v18 row_half_mirror row_mask:0xf bank_mask:0xf bound_ctrl:1
	v_add_f32_dpp v197, v197, v197 row_ror:8 row_mask:0xf bank_mask:0xc bound_ctrl:1
	v_add_f32_dpp v197, v189, v189 row_ror:8 row_mask:0xf bank_mask:0x3 bound_ctrl:1
	v_add_f32_dpp v18, v18, v18 row_ror:8 row_mask:0xf bank_mask:0xf bound_ctrl:1
	v_pk_fma_f32 v[0:1], v[92:93], v[18:19], v[4:5] op_sel_hi:[1,0,1] neg_lo:[1,0,0] neg_hi:[1,0,0]
	v_pk_fma_f32 v[2:3], v[94:95], v[18:19], v[6:7] op_sel_hi:[1,0,1] neg_lo:[1,0,0] neg_hi:[1,0,0]
	s_waitcnt lgkmcnt(6)
	v_pk_mul_f32 v[8:9], v[118:119], v[126:127] op_sel_hi:[1,0]
	v_pk_mul_f32 v[10:11], v[120:121], v[126:127] op_sel_hi:[1,0]
	ds_read_b128 v[74:77], v141 offset:2112
	ds_read_b32 v82, v142 offset:1344
	ds_read_b128 v[66:69], v141 offset:1600
	ds_read_b128 v[62:65], v141 offset:1344
	ds_read_b128 v[70:73], v141 offset:1856
	ds_read_b128 v[78:81], v141 offset:2368
	v_pk_mul_f32 v[16:17], v[0:1], v[110:111]
	v_pk_fma_f32 v[16:17], v[2:3], v[112:113], v[16:17]
	v_add_f32_e32 v18, v16, v17
	v_pk_mul_f32 v[20:21], v[0:1], v[100:101]
	v_pk_fma_f32 v[4:5], v[0:1], v[106:107], v[8:9]
	v_add_f32_dpp v18, v18, v18 quad_perm:[1,0,3,2] row_mask:0xf bank_mask:0xf bound_ctrl:1
	v_pk_fma_f32 v[20:21], v[2:3], v[102:103], v[20:21]
	v_add_f32_e32 v200, v20, v21
	v_add_f32_dpp v18, v18, v18 quad_perm:[2,3,0,1] row_mask:0xf bank_mask:0xf bound_ctrl:1
	s_nop 0
	v_pk_fma_f32 v[6:7], v[2:3], v[108:109], v[10:11]
	v_add_f32_dpp v18, v18, v18 row_half_mirror row_mask:0xf bank_mask:0xf bound_ctrl:1
	v_add_f32_dpp v200, v200, v200 row_ror:8 row_mask:0xf bank_mask:0xc bound_ctrl:1
	v_add_f32_dpp v200, v190, v190 row_ror:8 row_mask:0xf bank_mask:0x3 bound_ctrl:1
	v_add_f32_dpp v18, v18, v18 row_ror:8 row_mask:0xf bank_mask:0xf bound_ctrl:1
	v_pk_fma_f32 v[0:1], v[114:115], v[18:19], v[4:5] op_sel_hi:[1,0,1] neg_lo:[1,0,0] neg_hi:[1,0,0]
	v_pk_fma_f32 v[2:3], v[116:117], v[18:19], v[6:7] op_sel_hi:[1,0,1] neg_lo:[1,0,0] neg_hi:[1,0,0]
	s_waitcnt lgkmcnt(6)
	v_pk_mul_f32 v[8:9], v[52:53], v[60:61] op_sel_hi:[1,0]
	v_pk_mul_f32 v[10:11], v[54:55], v[60:61] op_sel_hi:[1,0]
	s_add_i32 s4, s4, 1
	s_mov_b32 s0, s6
	s_mov_b32 s6, s7
	s_mov_b32 s7, s25
	s_mov_b32 s25, s0
	v_mov_b32_e32 v139, v141
	v_mov_b32_e32 v140, v142
	v_add_u32_e32 v141, s7, v24
	v_add_u32_e32 v142, s7, v25
	v_add_u32_e32 v143, s7, v26
	v_add_u32_e32 v35, s7, v27
	s_cmp_lt_u32 s4, s5
	s_cbranch_scc1 .Lscan_chunk
	v_mul_f32_e32 v201, v0, v122
	v_fmac_f32_e32 v201, v1, v123
	v_fmac_f32_e32 v201, v2, v124
	v_fmac_f32_e32 v201, v3, v125
	s_nop 1
	v_add_f32_dpp v201, v201, v201 row_ror:8 row_mask:0xf bank_mask:0xc bound_ctrl:1
	v_add_f32_dpp v201, v191, v191 row_ror:8 row_mask:0xf bank_mask:0x3 bound_ctrl:1
	s_nop 1
	v_add_f32_dpp v196, v196, v196 row_half_mirror row_mask:0xf bank_mask:0xa bound_ctrl:1
	v_add_f32_dpp v196, v192, v192 row_half_mirror row_mask:0xf bank_mask:0x5 bound_ctrl:1
	v_add_f32_dpp v197, v197, v197 row_half_mirror row_mask:0xf bank_mask:0xa bound_ctrl:1
	v_add_f32_dpp v197, v193, v193 row_half_mirror row_mask:0xf bank_mask:0x5 bound_ctrl:1
	v_add_f32_dpp v200, v200, v200 row_half_mirror row_mask:0xf bank_mask:0xa bound_ctrl:1
	v_add_f32_dpp v200, v194, v194 row_half_mirror row_mask:0xf bank_mask:0x5 bound_ctrl:1
	v_add_f32_dpp v201, v201, v201 row_half_mirror row_mask:0xf bank_mask:0xa bound_ctrl:1
	v_add_f32_dpp v201, v195, v195 row_half_mirror row_mask:0xf bank_mask:0x5 bound_ctrl:1
	s_nop 1
	v_cndmask_b32_e64 v22, v196, v200, s[36:37]
	v_cndmask_b32_e64 v202, v200, v196, s[36:37]
	s_nop 1
	v_add_f32_dpp v200, v202, v22 quad_perm:[2,3,0,1] row_mask:0xf bank_mask:0xf bound_ctrl:1
	v_cndmask_b32_e64 v203, v197, v201, s[36:37]
	v_cndmask_b32_e64 v202, v201, v197, s[36:37]
	s_nop 1
	v_add_f32_dpp v201, v202, v203 quad_perm:[2,3,0,1] row_mask:0xf bank_mask:0xf bound_ctrl:1
	v_cndmask_b32_e64 v22, v200, v201, s[38:39]
	v_cndmask_b32_e64 v202, v201, v200, s[38:39]
	s_nop 1
	v_add_f32_dpp v23, v202, v22 quad_perm:[1,0,3,2] row_mask:0xf bank_mask:0xf bound_ctrl:1
	global_store_dword v138, v23, s[96:97]
	s_cmp_eq_u32 s28, 0
	s_cbranch_scc1 .Lscan_done
	v_readlane_b32 s0, v254, 57
	v_readlane_b32 s1, v254, 58
	s_nop 4
	global_store_dwordx4 v39, v[0:3], s[0:1]
